# weights transposes (w_in, w_gate_up with gain): all 32+32 loads issued before first wait instead of one round trip per element
# speedup vs baseline: 1.0164x; 1.0164x over previous
.LBB0_71:
	s_andn2_saveexec_b64 s[2:3], s[2:3]
	v_lshrrev_b32_e32 v18, 1, v18
	v_and_b32_e32 v18, 28, v18
	v_or_b32_e32 v19, v18, v22
	v_add_u32_e32 v18, v97, v18
	v_and_b32_e32 v17, 0xffffffc0, v17
	v_cndmask_b32_e64 v18, v18, v19, s[4:5]
	v_add_u32_e32 v18, v18, v17
	s_or_b64 exec, exec, s[2:3]
	v_lshlrev_b32_e32 v16, 6, v16
	v_ashrrev_i32_e32 v19, 31, v18
	v_ashrrev_i32_e32 v17, 31, v16
	v_lshl_add_u64 v[18:19], v[18:19], 2, s[40:41]
	v_lshl_add_u64 v[100:101], v[16:17], 0, v[4:5]
	v_lshl_add_u64 v[100:101], v[100:101], 2, s[38:39]
	global_load_dword v126, v[100:101], off
	global_load_dword v127, v[100:101], off offset:8
	global_load_dword v128, v[100:101], off offset:16
	global_load_dword v129, v[100:101], off offset:24
	global_load_dword v130, v[100:101], off offset:32
	global_load_dword v131, v[100:101], off offset:40
	global_load_dword v132, v[100:101], off offset:48
	global_load_dword v133, v[100:101], off offset:56
	global_load_dword v134, v[100:101], off offset:64
	global_load_dword v135, v[100:101], off offset:72
	global_load_dword v136, v[100:101], off offset:80
	global_load_dword v137, v[100:101], off offset:88
	global_load_dword v138, v[100:101], off offset:96
	global_load_dword v139, v[100:101], off offset:104
	global_load_dword v140, v[100:101], off offset:112
	global_load_dword v141, v[100:101], off offset:120
	global_load_dword v142, v[100:101], off offset:128
	global_load_dword v143, v[100:101], off offset:136
	global_load_dword v144, v[100:101], off offset:144
	global_load_dword v145, v[100:101], off offset:152
	global_load_dword v146, v[100:101], off offset:160
	global_load_dword v147, v[100:101], off offset:168
	global_load_dword v148, v[100:101], off offset:176
	global_load_dword v149, v[100:101], off offset:184
	global_load_dword v150, v[100:101], off offset:192
	global_load_dword v151, v[100:101], off offset:200
	global_load_dword v152, v[100:101], off offset:208
	global_load_dword v153, v[100:101], off offset:216
	global_load_dword v154, v[100:101], off offset:224
	global_load_dword v155, v[100:101], off offset:232
	global_load_dword v156, v[100:101], off offset:240
	global_load_dword v157, v[100:101], off offset:248
	v_or_b32_e32 v20, v16, v4
	v_mad_i64_i32 v[102:103], s[2:3], v20, s26, v[18:19]
	global_load_dword v158, v[102:103], off
	v_or_b32_e32 v20, v16, v27
	v_mad_i64_i32 v[102:103], s[2:3], v20, s26, v[18:19]
	global_load_dword v159, v[102:103], off
	v_or_b32_e32 v20, v16, v29
	v_mad_i64_i32 v[102:103], s[2:3], v20, s26, v[18:19]
	global_load_dword v160, v[102:103], off
	v_or_b32_e32 v20, v16, v31
	v_mad_i64_i32 v[102:103], s[2:3], v20, s26, v[18:19]
	global_load_dword v161, v[102:103], off
	v_or_b32_e32 v20, v16, v33
	v_mad_i64_i32 v[102:103], s[2:3], v20, s26, v[18:19]
	global_load_dword v162, v[102:103], off
	v_or_b32_e32 v20, v16, v35
	v_mad_i64_i32 v[102:103], s[2:3], v20, s26, v[18:19]
	global_load_dword v163, v[102:103], off
	v_or_b32_e32 v20, v16, v37
	v_mad_i64_i32 v[102:103], s[2:3], v20, s26, v[18:19]
	global_load_dword v164, v[102:103], off
	v_or_b32_e32 v20, v16, v39
	v_mad_i64_i32 v[102:103], s[2:3], v20, s26, v[18:19]
	global_load_dword v165, v[102:103], off
	v_or_b32_e32 v20, v16, v41
	v_mad_i64_i32 v[102:103], s[2:3], v20, s26, v[18:19]
	global_load_dword v166, v[102:103], off
	v_or_b32_e32 v20, v16, v43
	v_mad_i64_i32 v[102:103], s[2:3], v20, s26, v[18:19]
	global_load_dword v167, v[102:103], off
	v_or_b32_e32 v20, v16, v45
	v_mad_i64_i32 v[102:103], s[2:3], v20, s26, v[18:19]
	global_load_dword v168, v[102:103], off
	v_or_b32_e32 v20, v16, v47
	v_mad_i64_i32 v[102:103], s[2:3], v20, s26, v[18:19]
	global_load_dword v169, v[102:103], off
	v_or_b32_e32 v20, v16, v49
	v_mad_i64_i32 v[102:103], s[2:3], v20, s26, v[18:19]
	global_load_dword v170, v[102:103], off
	v_or_b32_e32 v20, v16, v51
	v_mad_i64_i32 v[102:103], s[2:3], v20, s26, v[18:19]
	global_load_dword v171, v[102:103], off
	v_or_b32_e32 v20, v16, v53
	v_mad_i64_i32 v[102:103], s[2:3], v20, s26, v[18:19]
	global_load_dword v172, v[102:103], off
	v_or_b32_e32 v20, v16, v55
	v_mad_i64_i32 v[102:103], s[2:3], v20, s26, v[18:19]
	global_load_dword v173, v[102:103], off
	v_or_b32_e32 v20, v16, v57
	v_mad_i64_i32 v[102:103], s[2:3], v20, s26, v[18:19]
	global_load_dword v174, v[102:103], off
	v_or_b32_e32 v20, v16, v59
	v_mad_i64_i32 v[102:103], s[2:3], v20, s26, v[18:19]
	global_load_dword v175, v[102:103], off
	v_or_b32_e32 v20, v16, v66
	v_mad_i64_i32 v[102:103], s[2:3], v20, s26, v[18:19]
	global_load_dword v176, v[102:103], off
	v_or_b32_e32 v20, v16, v68
	v_mad_i64_i32 v[102:103], s[2:3], v20, s26, v[18:19]
	global_load_dword v177, v[102:103], off
	v_or_b32_e32 v20, v16, v70
	v_mad_i64_i32 v[102:103], s[2:3], v20, s26, v[18:19]
	global_load_dword v178, v[102:103], off
	v_or_b32_e32 v20, v16, v72
	v_mad_i64_i32 v[102:103], s[2:3], v20, s26, v[18:19]
	global_load_dword v179, v[102:103], off
	v_or_b32_e32 v20, v16, v74
	v_mad_i64_i32 v[102:103], s[2:3], v20, s26, v[18:19]
	global_load_dword v180, v[102:103], off
	v_or_b32_e32 v20, v16, v76
	v_mad_i64_i32 v[102:103], s[2:3], v20, s26, v[18:19]
	global_load_dword v181, v[102:103], off
	s_waitcnt vmcnt(24)
	v_or_b32_e32 v20, v16, v78
	v_mad_i64_i32 v[102:103], s[2:3], v20, s26, v[18:19]
	global_load_dword v182, v[102:103], off
	v_or_b32_e32 v20, v16, v80
	v_mad_i64_i32 v[102:103], s[2:3], v20, s26, v[18:19]
	global_load_dword v183, v[102:103], off
	v_or_b32_e32 v20, v16, v82
	v_mad_i64_i32 v[102:103], s[2:3], v20, s26, v[18:19]
	global_load_dword v184, v[102:103], off
	v_or_b32_e32 v20, v16, v84
	v_mad_i64_i32 v[102:103], s[2:3], v20, s26, v[18:19]
	global_load_dword v185, v[102:103], off
	v_or_b32_e32 v20, v16, v86
	v_mad_i64_i32 v[102:103], s[2:3], v20, s26, v[18:19]
	global_load_dword v186, v[102:103], off
	v_or_b32_e32 v20, v16, v88
	v_mad_i64_i32 v[102:103], s[2:3], v20, s26, v[18:19]
	global_load_dword v187, v[102:103], off
	v_or_b32_e32 v20, v16, v90
	v_mad_i64_i32 v[102:103], s[2:3], v20, s26, v[18:19]
	global_load_dword v188, v[102:103], off
	v_or_b32_e32 v20, v16, v92
	v_mad_i64_i32 v[102:103], s[2:3], v20, s26, v[18:19]
	global_load_dword v189, v[102:103], off
	s_waitcnt vmcnt(31)
	v_mul_f32_e32 v158, v158, v126
	ds_write_b32 v26, v158
	s_waitcnt vmcnt(30)
	v_mul_f32_e32 v159, v159, v127
	ds_write_b32 v28, v159
	s_waitcnt vmcnt(29)
	v_mul_f32_e32 v160, v160, v128
	ds_write_b32 v30, v160
	s_waitcnt vmcnt(28)
	v_mul_f32_e32 v161, v161, v129
	ds_write_b32 v32, v161
	s_waitcnt vmcnt(27)
	v_mul_f32_e32 v162, v162, v130
	ds_write_b32 v34, v162
	s_waitcnt vmcnt(26)
	v_mul_f32_e32 v163, v163, v131
	ds_write_b32 v36, v163
	s_waitcnt vmcnt(25)
	v_mul_f32_e32 v164, v164, v132
	ds_write_b32 v38, v164
	s_waitcnt vmcnt(24)
	v_mul_f32_e32 v165, v165, v133
	ds_write_b32 v40, v165
	s_waitcnt vmcnt(23)
	v_mul_f32_e32 v166, v166, v134
	ds_write_b32 v42, v166
	s_waitcnt vmcnt(22)
	v_mul_f32_e32 v167, v167, v135
	ds_write_b32 v44, v167
	s_waitcnt vmcnt(21)
	v_mul_f32_e32 v168, v168, v136
	ds_write_b32 v46, v168
	s_waitcnt vmcnt(20)
	v_mul_f32_e32 v169, v169, v137
	ds_write_b32 v48, v169
	s_waitcnt vmcnt(19)
	v_mul_f32_e32 v170, v170, v138
	ds_write_b32 v50, v170
	s_waitcnt vmcnt(18)
	v_mul_f32_e32 v171, v171, v139
	ds_write_b32 v52, v171
	s_waitcnt vmcnt(17)
	v_mul_f32_e32 v172, v172, v140
	ds_write_b32 v54, v172
	s_waitcnt vmcnt(16)
	v_mul_f32_e32 v173, v173, v141
	ds_write_b32 v56, v173
	s_waitcnt vmcnt(15)
	v_mul_f32_e32 v174, v174, v142
	ds_write_b32 v58, v174
	s_waitcnt vmcnt(14)
	v_mul_f32_e32 v175, v175, v143
	ds_write_b32 v60, v175
	s_waitcnt vmcnt(13)
	v_mul_f32_e32 v176, v176, v144
	ds_write_b32 v67, v176
	s_waitcnt vmcnt(12)
	v_mul_f32_e32 v177, v177, v145
	ds_write_b32 v69, v177
	s_waitcnt vmcnt(11)
	v_mul_f32_e32 v178, v178, v146
	ds_write_b32 v71, v178
	s_waitcnt vmcnt(10)
	v_mul_f32_e32 v179, v179, v147
	ds_write_b32 v73, v179
	s_waitcnt vmcnt(9)
	v_mul_f32_e32 v180, v180, v148
	ds_write_b32 v75, v180
	s_waitcnt vmcnt(8)
	v_mul_f32_e32 v181, v181, v149
	ds_write_b32 v77, v181
	s_waitcnt vmcnt(7)
	v_mul_f32_e32 v182, v182, v150
	ds_write_b32 v79, v182
	s_waitcnt vmcnt(6)
	v_mul_f32_e32 v183, v183, v151
	ds_write_b32 v81, v183
	s_waitcnt vmcnt(5)
	v_mul_f32_e32 v184, v184, v152
	ds_write_b32 v83, v184
	s_waitcnt vmcnt(4)
	v_mul_f32_e32 v185, v185, v153
	ds_write_b32 v85, v185
	s_waitcnt vmcnt(3)
	v_mul_f32_e32 v186, v186, v154
	ds_write_b32 v87, v186
	s_waitcnt vmcnt(2)
	v_mul_f32_e32 v187, v187, v155
	ds_write_b32 v89, v187
	s_waitcnt vmcnt(1)
	v_mul_f32_e32 v188, v188, v156
	ds_write_b32 v91, v188
	s_waitcnt vmcnt(0)
	v_mul_f32_e32 v19, v189, v157
	s_branch .LBB0_54

.LBB0_879:
	s_andn2_saveexec_b64 s[14:15], s[2:3]
	s_cbranch_execz .LBB0_876
	v_mul_hi_i32 v2, v9, s21
	v_lshrrev_b32_e32 v10, 31, v2
	v_ashrrev_i32_e32 v2, 5, v2
	v_add_u32_e32 v11, v2, v10
	v_mul_lo_u32 v2, v11, s18
	v_add_u32_e32 v12, v16, v85
	v_add3_u32 v14, v12, v2, s22
	v_mad_u64_u32 v[12:13], s[2:3], v11, s23, v[8:9]
	v_lshlrev_b32_e32 v10, 6, v11
	v_and_b32_e32 v11, 0xffffff80, v12
	v_and_b32_e32 v12, 4, v9
	v_and_b32_e32 v13, 0x7b, v14
	v_or3_b32 v11, v11, v12, v13
	v_add_u32_e32 v12, 0xb00, v11
	v_cndmask_b32_e64 v12, v12, v11, s[6:7]
	v_ashrrev_i32_e32 v13, 31, v12
	v_lshl_add_u64 v[12:13], v[12:13], 2, s[74:75]
	v_ashrrev_i32_e32 v11, 31, v10
	v_lshl_add_u64 v[88:89], v[10:11], 0, v[0:1]
	v_lshl_add_u64 v[88:89], v[88:89], 2, s[72:73]
	global_load_dword v116, v[88:89], off
	global_load_dword v117, v[88:89], off offset:8
	global_load_dword v118, v[88:89], off offset:16
	global_load_dword v119, v[88:89], off offset:24
	global_load_dword v120, v[88:89], off offset:32
	global_load_dword v121, v[88:89], off offset:40
	global_load_dword v122, v[88:89], off offset:48
	global_load_dword v123, v[88:89], off offset:56
	global_load_dword v124, v[88:89], off offset:64
	global_load_dword v125, v[88:89], off offset:72
	global_load_dword v126, v[88:89], off offset:80
	global_load_dword v127, v[88:89], off offset:88
	global_load_dword v128, v[88:89], off offset:96
	global_load_dword v129, v[88:89], off offset:104
	global_load_dword v130, v[88:89], off offset:112
	global_load_dword v131, v[88:89], off offset:120
	global_load_dword v132, v[88:89], off offset:128
	global_load_dword v133, v[88:89], off offset:136
	global_load_dword v134, v[88:89], off offset:144
	global_load_dword v135, v[88:89], off offset:152
	global_load_dword v136, v[88:89], off offset:160
	global_load_dword v137, v[88:89], off offset:168
	global_load_dword v138, v[88:89], off offset:176
	global_load_dword v139, v[88:89], off offset:184
	global_load_dword v140, v[88:89], off offset:192
	global_load_dword v141, v[88:89], off offset:200
	global_load_dword v142, v[88:89], off offset:208
	global_load_dword v143, v[88:89], off offset:216
	global_load_dword v144, v[88:89], off offset:224
	global_load_dword v145, v[88:89], off offset:232
	global_load_dword v146, v[88:89], off offset:240
	global_load_dword v147, v[88:89], off offset:248
	v_or_b32_e32 v14, v10, v0
	v_mad_i64_i32 v[90:91], s[2:3], v14, s24, v[12:13]
	global_load_dword v148, v[90:91], off
	v_or_b32_e32 v14, v10, v18
	v_mad_i64_i32 v[90:91], s[2:3], v14, s24, v[12:13]
	global_load_dword v149, v[90:91], off
	v_or_b32_e32 v14, v10, v20
	v_mad_i64_i32 v[90:91], s[2:3], v14, s24, v[12:13]
	global_load_dword v150, v[90:91], off
	v_or_b32_e32 v14, v10, v22
	v_mad_i64_i32 v[90:91], s[2:3], v14, s24, v[12:13]
	global_load_dword v151, v[90:91], off
	v_or_b32_e32 v14, v10, v24
	v_mad_i64_i32 v[90:91], s[2:3], v14, s24, v[12:13]
	global_load_dword v152, v[90:91], off
	v_or_b32_e32 v14, v10, v26
	v_mad_i64_i32 v[90:91], s[2:3], v14, s24, v[12:13]
	global_load_dword v153, v[90:91], off
	v_or_b32_e32 v14, v10, v28
	v_mad_i64_i32 v[90:91], s[2:3], v14, s24, v[12:13]
	global_load_dword v154, v[90:91], off
	v_or_b32_e32 v14, v10, v30
	v_mad_i64_i32 v[90:91], s[2:3], v14, s24, v[12:13]
	global_load_dword v155, v[90:91], off
	v_or_b32_e32 v14, v10, v32
	v_mad_i64_i32 v[90:91], s[2:3], v14, s24, v[12:13]
	global_load_dword v156, v[90:91], off
	v_or_b32_e32 v14, v10, v34
	v_mad_i64_i32 v[90:91], s[2:3], v14, s24, v[12:13]
	global_load_dword v157, v[90:91], off
	v_or_b32_e32 v14, v10, v36
	v_mad_i64_i32 v[90:91], s[2:3], v14, s24, v[12:13]
	global_load_dword v158, v[90:91], off
	v_or_b32_e32 v14, v10, v38
	v_mad_i64_i32 v[90:91], s[2:3], v14, s24, v[12:13]
	global_load_dword v159, v[90:91], off
	v_or_b32_e32 v14, v10, v40
	v_mad_i64_i32 v[90:91], s[2:3], v14, s24, v[12:13]
	global_load_dword v160, v[90:91], off
	v_or_b32_e32 v14, v10, v42
	v_mad_i64_i32 v[90:91], s[2:3], v14, s24, v[12:13]
	global_load_dword v161, v[90:91], off
	v_or_b32_e32 v14, v10, v44
	v_mad_i64_i32 v[90:91], s[2:3], v14, s24, v[12:13]
	global_load_dword v162, v[90:91], off
	v_or_b32_e32 v14, v10, v46
	v_mad_i64_i32 v[90:91], s[2:3], v14, s24, v[12:13]
	global_load_dword v163, v[90:91], off
	v_or_b32_e32 v14, v10, v48
	v_mad_i64_i32 v[90:91], s[2:3], v14, s24, v[12:13]
	global_load_dword v164, v[90:91], off
	v_or_b32_e32 v14, v10, v50
	v_mad_i64_i32 v[90:91], s[2:3], v14, s24, v[12:13]
	global_load_dword v165, v[90:91], off
	v_or_b32_e32 v14, v10, v52
	v_mad_i64_i32 v[90:91], s[2:3], v14, s24, v[12:13]
	global_load_dword v166, v[90:91], off
	v_or_b32_e32 v14, v10, v54
	v_mad_i64_i32 v[90:91], s[2:3], v14, s24, v[12:13]
	global_load_dword v167, v[90:91], off
	v_or_b32_e32 v14, v10, v56
	v_mad_i64_i32 v[90:91], s[2:3], v14, s24, v[12:13]
	global_load_dword v168, v[90:91], off
	v_or_b32_e32 v14, v10, v58
	v_mad_i64_i32 v[90:91], s[2:3], v14, s24, v[12:13]
	global_load_dword v169, v[90:91], off
	v_or_b32_e32 v14, v10, v60
	v_mad_i64_i32 v[90:91], s[2:3], v14, s24, v[12:13]
	global_load_dword v170, v[90:91], off
	v_or_b32_e32 v14, v10, v62
	v_mad_i64_i32 v[90:91], s[2:3], v14, s24, v[12:13]
	global_load_dword v171, v[90:91], off
	s_waitcnt vmcnt(24)
	v_or_b32_e32 v14, v10, v64
	v_mad_i64_i32 v[90:91], s[2:3], v14, s24, v[12:13]
	global_load_dword v172, v[90:91], off
	v_or_b32_e32 v14, v10, v66
	v_mad_i64_i32 v[90:91], s[2:3], v14, s24, v[12:13]
	global_load_dword v173, v[90:91], off
	v_or_b32_e32 v14, v10, v68
	v_mad_i64_i32 v[90:91], s[2:3], v14, s24, v[12:13]
	global_load_dword v174, v[90:91], off
	v_or_b32_e32 v14, v10, v70
	v_mad_i64_i32 v[90:91], s[2:3], v14, s24, v[12:13]
	global_load_dword v175, v[90:91], off
	v_or_b32_e32 v14, v10, v72
	v_mad_i64_i32 v[90:91], s[2:3], v14, s24, v[12:13]
	global_load_dword v176, v[90:91], off
	v_or_b32_e32 v14, v10, v74
	v_mad_i64_i32 v[90:91], s[2:3], v14, s24, v[12:13]
	global_load_dword v177, v[90:91], off
	v_or_b32_e32 v14, v10, v76
	v_mad_i64_i32 v[90:91], s[2:3], v14, s24, v[12:13]
	global_load_dword v178, v[90:91], off
	v_or_b32_e32 v14, v10, v78
	v_mad_i64_i32 v[90:91], s[2:3], v14, s24, v[12:13]
	global_load_dword v179, v[90:91], off
	s_waitcnt vmcnt(31)
	v_mul_f32_e32 v148, v148, v116
	ds_write_b32 v17, v148
	s_waitcnt vmcnt(30)
	v_mul_f32_e32 v149, v149, v117
	ds_write_b32 v19, v149
	s_waitcnt vmcnt(29)
	v_mul_f32_e32 v150, v150, v118
	ds_write_b32 v21, v150
	s_waitcnt vmcnt(28)
	v_mul_f32_e32 v151, v151, v119
	ds_write_b32 v23, v151
	s_waitcnt vmcnt(27)
	v_mul_f32_e32 v152, v152, v120
	ds_write_b32 v25, v152
	s_waitcnt vmcnt(26)
	v_mul_f32_e32 v153, v153, v121
	ds_write_b32 v27, v153
	s_waitcnt vmcnt(25)
	v_mul_f32_e32 v154, v154, v122
	ds_write_b32 v29, v154
	s_waitcnt vmcnt(24)
	v_mul_f32_e32 v155, v155, v123
	ds_write_b32 v31, v155
	s_waitcnt vmcnt(23)
	v_mul_f32_e32 v156, v156, v124
	ds_write_b32 v33, v156
	s_waitcnt vmcnt(22)
	v_mul_f32_e32 v157, v157, v125
	ds_write_b32 v35, v157
	s_waitcnt vmcnt(21)
	v_mul_f32_e32 v158, v158, v126
	ds_write_b32 v37, v158
	s_waitcnt vmcnt(20)
	v_mul_f32_e32 v159, v159, v127
	ds_write_b32 v39, v159
	s_waitcnt vmcnt(19)
	v_mul_f32_e32 v160, v160, v128
	ds_write_b32 v41, v160
	s_waitcnt vmcnt(18)
	v_mul_f32_e32 v161, v161, v129
	ds_write_b32 v43, v161
	s_waitcnt vmcnt(17)
	v_mul_f32_e32 v162, v162, v130
	ds_write_b32 v45, v162
	s_waitcnt vmcnt(16)
	v_mul_f32_e32 v163, v163, v131
	ds_write_b32 v47, v163
	s_waitcnt vmcnt(15)
	v_mul_f32_e32 v164, v164, v132
	ds_write_b32 v49, v164
	s_waitcnt vmcnt(14)
	v_mul_f32_e32 v165, v165, v133
	ds_write_b32 v51, v165
	s_waitcnt vmcnt(13)
	v_mul_f32_e32 v166, v166, v134
	ds_write_b32 v53, v166
	s_waitcnt vmcnt(12)
	v_mul_f32_e32 v167, v167, v135
	ds_write_b32 v55, v167
	s_waitcnt vmcnt(11)
	v_mul_f32_e32 v168, v168, v136
	ds_write_b32 v57, v168
	s_waitcnt vmcnt(10)
	v_mul_f32_e32 v169, v169, v137
	ds_write_b32 v59, v169
	s_waitcnt vmcnt(9)
	v_mul_f32_e32 v170, v170, v138
	ds_write_b32 v61, v170
	s_waitcnt vmcnt(8)
	v_mul_f32_e32 v171, v171, v139
	ds_write_b32 v63, v171
	s_waitcnt vmcnt(7)
	v_mul_f32_e32 v172, v172, v140
	ds_write_b32 v65, v172
	s_waitcnt vmcnt(6)
	v_mul_f32_e32 v173, v173, v141
	ds_write_b32 v67, v173
	s_waitcnt vmcnt(5)
	v_mul_f32_e32 v174, v174, v142
	ds_write_b32 v69, v174
	s_waitcnt vmcnt(4)
	v_mul_f32_e32 v175, v175, v143
	ds_write_b32 v71, v175
	s_waitcnt vmcnt(3)
	v_mul_f32_e32 v176, v176, v144
	ds_write_b32 v73, v176
	s_waitcnt vmcnt(2)
	v_mul_f32_e32 v177, v177, v145
	ds_write_b32 v75, v177
	s_waitcnt vmcnt(1)
	v_mul_f32_e32 v178, v178, v146
	ds_write_b32 v77, v178
	s_waitcnt vmcnt(0)
	v_mul_f32_e32 v13, v179, v147
	s_branch .LBB0_875
